# peel first K-loop iteration of GU and in-proj GEMMs: first MFMA per accumulator quad takes SrcC=0, accumulator zeroing removed
# speedup vs baseline: 1.0133x; 1.0000x over previous
.LBB0_245:
	s_ashr_i32 s21, s20, 31
	s_lshl_b64 s[22:23], s[20:21], 19
	s_add_u32 s22, s37, s22
	s_addc_u32 s23, s38, s23
	s_and_b64 s[24:25], s[0:1], exec
	s_cselect_b32 s21, s23, s29
	s_cselect_b32 s58, s22, s28
	s_ashr_i32 s19, s18, 31
	s_lshl_b64 s[24:25], s[18:19], 19
	s_add_u32 s24, s39, s24
	s_addc_u32 s25, s40, s25
	s_and_b64 s[34:35], s[0:1], exec
	s_cselect_b32 s19, s25, s31
	s_cselect_b32 s59, s24, s30
	s_add_u32 s28, s28, 0x40080
	s_addc_u32 s29, s29, 0
	s_add_u32 s60, s30, 0x100
	v_mov_b32_e32 v0, 0
	s_addc_u32 s61, s31, 0
	s_mov_b32 s62, -2
	s_add_u32 s8, s28, 0xfffc0080
	s_addc_u32 s9, s29, -1
	s_add_i32 s63, 0, 0x10000
	s_cmp_eq_u32 s62, 12
	s_cselect_b32 s35, s21, s9
	s_cselect_b32 s34, s58, s8
	s_cselect_b32 s31, s19, s61
	s_cselect_b32 s30, s59, s60
	s_add_i32 s8, 0, 0x14000
	v_add_u32_e32 v156, s63, v145
	v_add_u32_e32 v172, s8, v145
	ds_read_b128 v[140:143], v156
	ds_read_b128 v[148:151], v156 offset:1024
	ds_read_b128 v[152:155], v156 offset:2048
	ds_read_b128 v[156:159], v156 offset:3072
	ds_read_b128 v[160:163], v172
	ds_read_b128 v[164:167], v172 offset:1024
	ds_read_b128 v[168:171], v172 offset:2048
	ds_read_b128 v[172:175], v172 offset:3072
	v_lshl_add_u64 v[208:209], s[28:29], 0, v[136:137]
	s_add_i32 m0, s50, 0xc000
	ds_read_b128 v[176:179], v147
	ds_read_b128 v[180:183], v147 offset:1024
	ds_read_b128 v[184:187], v147 offset:2048
	ds_read_b128 v[188:191], v147 offset:3072
	ds_read_b128 v[192:195], v147 offset:4096
	ds_read_b128 v[196:199], v147 offset:5120
	ds_read_b128 v[200:203], v147 offset:6144
	ds_read_b128 v[204:207], v147 offset:7168
	global_load_lds_dwordx4 v[208:209], off
	v_lshl_add_u64 v[208:209], s[28:29], 0, v[138:139]
	s_add_i32 m0, s50, 0xe000
	s_nop 0
	global_load_lds_dwordx4 v[208:209], off
	s_waitcnt vmcnt(8)
	s_waitcnt lgkmcnt(0)
	s_barrier
	s_setprio 1
	s_waitcnt lgkmcnt(0)
	v_mfma_f32_16x16x32_bf16 v[126:129], v[140:143], v[176:179], 0
	v_mfma_f32_16x16x32_bf16 v[118:121], v[152:155], v[176:179], 0
	v_mfma_f32_16x16x32_bf16 v[110:113], v[140:143], v[184:187], 0
	v_mfma_f32_16x16x32_bf16 v[102:105], v[152:155], v[184:187], 0
	v_mfma_f32_16x16x32_bf16 v[94:97], v[140:143], v[192:195], 0
	v_mfma_f32_16x16x32_bf16 v[86:89], v[152:155], v[192:195], 0
	v_mfma_f32_16x16x32_bf16 v[78:81], v[140:143], v[200:203], 0
	v_mfma_f32_16x16x32_bf16 v[70:73], v[152:155], v[200:203], 0
	v_mfma_f32_16x16x32_bf16 v[126:129], v[148:151], v[180:183], v[126:129]
	v_mfma_f32_16x16x32_bf16 v[118:121], v[156:159], v[180:183], v[118:121]
	v_mfma_f32_16x16x32_bf16 v[110:113], v[148:151], v[188:191], v[110:113]
	v_mfma_f32_16x16x32_bf16 v[102:105], v[156:159], v[188:191], v[102:105]
	v_mfma_f32_16x16x32_bf16 v[94:97], v[148:151], v[196:199], v[94:97]
	v_mfma_f32_16x16x32_bf16 v[86:89], v[156:159], v[196:199], v[86:89]
	v_mfma_f32_16x16x32_bf16 v[78:81], v[148:151], v[204:207], v[78:81]
	v_mfma_f32_16x16x32_bf16 v[70:73], v[156:159], v[204:207], v[70:73]
	s_setprio 0
	s_setprio 1
	v_mfma_f32_16x16x32_bf16 v[122:125], v[160:163], v[176:179], 0
	v_mfma_f32_16x16x32_bf16 v[114:117], v[168:171], v[176:179], 0
	v_mfma_f32_16x16x32_bf16 v[106:109], v[160:163], v[184:187], 0
	v_mfma_f32_16x16x32_bf16 v[98:101], v[168:171], v[184:187], 0
	v_mfma_f32_16x16x32_bf16 v[90:93], v[160:163], v[192:195], 0
	v_mfma_f32_16x16x32_bf16 v[82:85], v[168:171], v[192:195], 0
	v_mfma_f32_16x16x32_bf16 v[74:77], v[160:163], v[200:203], 0
	v_mfma_f32_16x16x32_bf16 v[66:69], v[168:171], v[200:203], 0
	v_mfma_f32_16x16x32_bf16 v[122:125], v[164:167], v[180:183], v[122:125]
	v_mfma_f32_16x16x32_bf16 v[114:117], v[172:175], v[180:183], v[114:117]
	v_mfma_f32_16x16x32_bf16 v[106:109], v[164:167], v[188:191], v[106:109]
	v_mfma_f32_16x16x32_bf16 v[98:101], v[172:175], v[188:191], v[98:101]
	v_mfma_f32_16x16x32_bf16 v[90:93], v[164:167], v[196:199], v[90:93]
	v_mfma_f32_16x16x32_bf16 v[82:85], v[172:175], v[196:199], v[82:85]
	v_mfma_f32_16x16x32_bf16 v[74:77], v[164:167], v[204:207], v[74:77]
	v_mfma_f32_16x16x32_bf16 v[66:69], v[172:175], v[204:207], v[66:69]
	s_setprio 0
	s_barrier
	s_add_i32 s9, s63, s41
	v_lshl_add_u64 v[208:209], s[30:31], 0, v[12:13]
	s_mov_b32 m0, s9
	ds_read_b128 v[176:179], v147 offset:16384
	ds_read_b128 v[180:183], v147 offset:17408
	ds_read_b128 v[184:187], v147 offset:18432
	ds_read_b128 v[188:191], v147 offset:19456
	ds_read_b128 v[192:195], v147 offset:20480
	ds_read_b128 v[196:199], v147 offset:21504
	ds_read_b128 v[200:203], v147 offset:22528
	ds_read_b128 v[204:207], v147 offset:23552
	global_load_lds_dwordx4 v[208:209], off
	s_add_i32 m0, s9, 0x2000
	s_add_u32 s64, s30, 0x40000
	v_lshl_add_u64 v[210:211], s[30:31], 0, v[130:131]
	s_addc_u32 s65, s31, 0
	s_add_i32 s8, s8, s41
	global_load_lds_dwordx4 v[210:211], off
	v_lshl_add_u64 v[212:213], s[64:65], 0, v[12:13]
	s_mov_b32 m0, s8
	v_lshl_add_u64 v[214:215], s[34:35], 0, v[132:133]
	global_load_lds_dwordx4 v[212:213], off
	v_lshl_add_u64 v[212:213], s[64:65], 0, v[130:131]
	s_add_i32 m0, s8, 0x2000
	s_nop 0
	global_load_lds_dwordx4 v[212:213], off
	v_lshl_add_u64 v[212:213], s[34:35], 0, v[134:135]
	s_mov_b32 m0, s50
	s_nop 0
	global_load_lds_dwordx4 v[212:213], off
	s_mov_b32 m0, s51
	s_nop 0
	global_load_lds_dwordx4 v[214:215], off
	s_waitcnt vmcnt(8)
	s_waitcnt lgkmcnt(0)
	s_barrier
	s_setprio 1
	s_waitcnt lgkmcnt(0)
	v_mfma_f32_16x16x32_bf16 v[62:65], v[140:143], v[176:179], 0
	v_mfma_f32_16x16x32_bf16 v[54:57], v[152:155], v[176:179], 0
	v_mfma_f32_16x16x32_bf16 v[46:49], v[140:143], v[184:187], 0
	v_mfma_f32_16x16x32_bf16 v[38:41], v[152:155], v[184:187], 0
	v_mfma_f32_16x16x32_bf16 v[30:33], v[140:143], v[192:195], 0
	v_mfma_f32_16x16x32_bf16 v[22:25], v[152:155], v[192:195], 0
	v_mfma_f32_16x16x32_bf16 v[14:17], v[140:143], v[200:203], 0
	v_mfma_f32_16x16x32_bf16 v[4:7], v[152:155], v[200:203], 0
	v_mfma_f32_16x16x32_bf16 v[62:65], v[148:151], v[180:183], v[62:65]
	v_mfma_f32_16x16x32_bf16 v[54:57], v[156:159], v[180:183], v[54:57]
	v_mfma_f32_16x16x32_bf16 v[46:49], v[148:151], v[188:191], v[46:49]
	v_mfma_f32_16x16x32_bf16 v[38:41], v[156:159], v[188:191], v[38:41]
	v_mfma_f32_16x16x32_bf16 v[30:33], v[148:151], v[196:199], v[30:33]
	v_mfma_f32_16x16x32_bf16 v[22:25], v[156:159], v[196:199], v[22:25]
	v_mfma_f32_16x16x32_bf16 v[14:17], v[148:151], v[204:207], v[14:17]
	v_mfma_f32_16x16x32_bf16 v[4:7], v[156:159], v[204:207], v[4:7]
	s_setprio 0
	s_setprio 1
	v_mfma_f32_16x16x32_bf16 v[58:61], v[160:163], v[176:179], 0
	v_mfma_f32_16x16x32_bf16 v[50:53], v[168:171], v[176:179], 0
	v_mfma_f32_16x16x32_bf16 v[42:45], v[160:163], v[184:187], 0
	v_mfma_f32_16x16x32_bf16 v[34:37], v[168:171], v[184:187], 0
	v_mfma_f32_16x16x32_bf16 v[26:29], v[160:163], v[192:195], 0
	v_mfma_f32_16x16x32_bf16 v[18:21], v[168:171], v[192:195], 0
	v_mfma_f32_16x16x32_bf16 v[8:11], v[160:163], v[200:203], 0
	v_mfma_f32_16x16x32_bf16 v[0:3], v[168:171], v[200:203], 0
	v_mfma_f32_16x16x32_bf16 v[58:61], v[164:167], v[180:183], v[58:61]
	v_mfma_f32_16x16x32_bf16 v[50:53], v[172:175], v[180:183], v[50:53]
	v_mfma_f32_16x16x32_bf16 v[42:45], v[164:167], v[188:191], v[42:45]
	v_mfma_f32_16x16x32_bf16 v[34:37], v[172:175], v[188:191], v[34:37]
	v_mfma_f32_16x16x32_bf16 v[26:29], v[164:167], v[196:199], v[26:29]
	v_mfma_f32_16x16x32_bf16 v[18:21], v[172:175], v[196:199], v[18:21]
	v_mfma_f32_16x16x32_bf16 v[8:11], v[164:167], v[204:207], v[8:11]
	v_mfma_f32_16x16x32_bf16 v[0:3], v[172:175], v[204:207], v[0:3]
	s_setprio 0
	s_barrier
	s_add_i32 s8, 0, 0x18000
	s_add_i32 s9, 0, 0x1c000
	v_add_u32_e32 v156, s8, v145
	v_add_u32_e32 v172, s9, v145
	ds_read_b128 v[140:143], v156
	ds_read_b128 v[148:151], v156 offset:1024
	ds_read_b128 v[152:155], v156 offset:2048
	ds_read_b128 v[156:159], v156 offset:3072
	ds_read_b128 v[160:163], v172
	ds_read_b128 v[164:167], v172 offset:1024
	ds_read_b128 v[168:171], v172 offset:2048
	ds_read_b128 v[172:175], v172 offset:3072
	s_add_u32 s34, s34, 0x40000
	s_addc_u32 s35, s35, 0
	s_mov_b32 m0, s52
	v_lshl_add_u64 v[228:229], s[34:35], 0, v[134:135]
	ds_read_b128 v[176:179], v147 offset:32768
	ds_read_b128 v[180:183], v147 offset:33792
	ds_read_b128 v[184:187], v147 offset:34816
	ds_read_b128 v[188:191], v147 offset:35840
	ds_read_b128 v[192:195], v147 offset:36864
	ds_read_b128 v[196:199], v147 offset:37888
	ds_read_b128 v[200:203], v147 offset:38912
	ds_read_b128 v[204:207], v147 offset:39936
	global_load_lds_dwordx4 v[228:229], off
	v_lshl_add_u64 v[228:229], s[34:35], 0, v[132:133]
	s_mov_b32 m0, s53
	s_nop 0
	global_load_lds_dwordx4 v[228:229], off
	s_waitcnt vmcnt(8)
	s_waitcnt lgkmcnt(0)
	s_barrier
	s_setprio 1
	s_waitcnt lgkmcnt(0)
	v_mfma_f32_16x16x32_bf16 v[126:129], v[140:143], v[176:179], v[126:129]
	v_mfma_f32_16x16x32_bf16 v[118:121], v[152:155], v[176:179], v[118:121]
	v_mfma_f32_16x16x32_bf16 v[110:113], v[140:143], v[184:187], v[110:113]
	v_mfma_f32_16x16x32_bf16 v[102:105], v[152:155], v[184:187], v[102:105]
	v_mfma_f32_16x16x32_bf16 v[94:97], v[140:143], v[192:195], v[94:97]
	v_mfma_f32_16x16x32_bf16 v[86:89], v[152:155], v[192:195], v[86:89]
	v_mfma_f32_16x16x32_bf16 v[78:81], v[140:143], v[200:203], v[78:81]
	v_mfma_f32_16x16x32_bf16 v[70:73], v[152:155], v[200:203], v[70:73]
	v_mfma_f32_16x16x32_bf16 v[126:129], v[148:151], v[180:183], v[126:129]
	v_mfma_f32_16x16x32_bf16 v[118:121], v[156:159], v[180:183], v[118:121]
	v_mfma_f32_16x16x32_bf16 v[110:113], v[148:151], v[188:191], v[110:113]
	v_mfma_f32_16x16x32_bf16 v[102:105], v[156:159], v[188:191], v[102:105]
	v_mfma_f32_16x16x32_bf16 v[94:97], v[148:151], v[196:199], v[94:97]
	v_mfma_f32_16x16x32_bf16 v[86:89], v[156:159], v[196:199], v[86:89]
	v_mfma_f32_16x16x32_bf16 v[78:81], v[148:151], v[204:207], v[78:81]
	v_mfma_f32_16x16x32_bf16 v[70:73], v[156:159], v[204:207], v[70:73]
	s_setprio 0
	s_setprio 1
	v_mfma_f32_16x16x32_bf16 v[122:125], v[160:163], v[176:179], v[122:125]
	v_mfma_f32_16x16x32_bf16 v[114:117], v[168:171], v[176:179], v[114:117]
	v_mfma_f32_16x16x32_bf16 v[106:109], v[160:163], v[184:187], v[106:109]
	v_mfma_f32_16x16x32_bf16 v[98:101], v[168:171], v[184:187], v[98:101]
	v_mfma_f32_16x16x32_bf16 v[90:93], v[160:163], v[192:195], v[90:93]
	v_mfma_f32_16x16x32_bf16 v[82:85], v[168:171], v[192:195], v[82:85]
	v_mfma_f32_16x16x32_bf16 v[74:77], v[160:163], v[200:203], v[74:77]
	v_mfma_f32_16x16x32_bf16 v[66:69], v[168:171], v[200:203], v[66:69]
	v_mfma_f32_16x16x32_bf16 v[122:125], v[164:167], v[180:183], v[122:125]
	v_mfma_f32_16x16x32_bf16 v[114:117], v[172:175], v[180:183], v[114:117]
	v_mfma_f32_16x16x32_bf16 v[106:109], v[164:167], v[188:191], v[106:109]
	v_mfma_f32_16x16x32_bf16 v[98:101], v[172:175], v[188:191], v[98:101]
	v_mfma_f32_16x16x32_bf16 v[90:93], v[164:167], v[196:199], v[90:93]
	v_mfma_f32_16x16x32_bf16 v[82:85], v[172:175], v[196:199], v[82:85]
	v_mfma_f32_16x16x32_bf16 v[74:77], v[164:167], v[204:207], v[74:77]
	v_mfma_f32_16x16x32_bf16 v[66:69], v[172:175], v[204:207], v[66:69]
	s_setprio 0
	s_barrier
	s_add_i32 s8, s8, s41
	v_lshl_add_u64 v[208:209], v[208:209], 0, s[42:43]
	s_mov_b32 m0, s8
	ds_read_b128 v[176:179], v147 offset:49152
	ds_read_b128 v[180:183], v147 offset:50176
	ds_read_b128 v[184:187], v147 offset:51200
	ds_read_b128 v[188:191], v147 offset:52224
	ds_read_b128 v[192:195], v147 offset:53248
	ds_read_b128 v[196:199], v147 offset:54272
	ds_read_b128 v[200:203], v147 offset:55296
	ds_read_b128 v[204:207], v147 offset:56320
	global_load_lds_dwordx4 v[208:209], off
	s_add_i32 m0, s8, 0x2000
	s_add_u32 s30, s30, 0x40080
	v_lshl_add_u64 v[208:209], v[210:211], 0, s[42:43]
	s_addc_u32 s31, s31, 0
	s_add_i32 s8, s9, s41
	global_load_lds_dwordx4 v[208:209], off
	v_lshl_add_u64 v[208:209], s[30:31], 0, v[12:13]
	s_mov_b32 m0, s8
	s_nop 0
	global_load_lds_dwordx4 v[208:209], off
	v_lshl_add_u64 v[208:209], s[30:31], 0, v[130:131]
	s_add_i32 m0, s8, 0x2000
	s_nop 0
	global_load_lds_dwordx4 v[208:209], off
	v_lshl_add_u64 v[208:209], v[212:213], 0, s[42:43]
	s_mov_b32 m0, s54
	s_nop 0
	global_load_lds_dwordx4 v[208:209], off
	v_lshl_add_u64 v[208:209], v[214:215], 0, s[42:43]
	s_mov_b32 m0, s55
	s_nop 0
	global_load_lds_dwordx4 v[208:209], off
	s_waitcnt vmcnt(8)
	s_waitcnt lgkmcnt(0)
	s_barrier
	s_setprio 1
	s_waitcnt lgkmcnt(0)
	v_mfma_f32_16x16x32_bf16 v[62:65], v[140:143], v[176:179], v[62:65]
	v_mfma_f32_16x16x32_bf16 v[54:57], v[152:155], v[176:179], v[54:57]
	v_mfma_f32_16x16x32_bf16 v[46:49], v[140:143], v[184:187], v[46:49]
	v_mfma_f32_16x16x32_bf16 v[38:41], v[152:155], v[184:187], v[38:41]
	v_mfma_f32_16x16x32_bf16 v[30:33], v[140:143], v[192:195], v[30:33]
	v_mfma_f32_16x16x32_bf16 v[22:25], v[152:155], v[192:195], v[22:25]
	v_mfma_f32_16x16x32_bf16 v[14:17], v[140:143], v[200:203], v[14:17]
	v_mfma_f32_16x16x32_bf16 v[4:7], v[152:155], v[200:203], v[4:7]
	v_mfma_f32_16x16x32_bf16 v[62:65], v[148:151], v[180:183], v[62:65]
	v_mfma_f32_16x16x32_bf16 v[54:57], v[156:159], v[180:183], v[54:57]
	v_mfma_f32_16x16x32_bf16 v[46:49], v[148:151], v[188:191], v[46:49]
	v_mfma_f32_16x16x32_bf16 v[38:41], v[156:159], v[188:191], v[38:41]
	v_mfma_f32_16x16x32_bf16 v[30:33], v[148:151], v[196:199], v[30:33]
	v_mfma_f32_16x16x32_bf16 v[22:25], v[156:159], v[196:199], v[22:25]
	v_mfma_f32_16x16x32_bf16 v[14:17], v[148:151], v[204:207], v[14:17]
	v_mfma_f32_16x16x32_bf16 v[4:7], v[156:159], v[204:207], v[4:7]
	s_setprio 0
	s_setprio 1
	v_mfma_f32_16x16x32_bf16 v[58:61], v[160:163], v[176:179], v[58:61]
	v_mfma_f32_16x16x32_bf16 v[50:53], v[168:171], v[176:179], v[50:53]
	v_mfma_f32_16x16x32_bf16 v[42:45], v[160:163], v[184:187], v[42:45]
	v_mfma_f32_16x16x32_bf16 v[34:37], v[168:171], v[184:187], v[34:37]
	v_mfma_f32_16x16x32_bf16 v[26:29], v[160:163], v[192:195], v[26:29]
	v_mfma_f32_16x16x32_bf16 v[18:21], v[168:171], v[192:195], v[18:21]
	v_mfma_f32_16x16x32_bf16 v[8:11], v[160:163], v[200:203], v[8:11]
	v_mfma_f32_16x16x32_bf16 v[0:3], v[168:171], v[200:203], v[0:3]
	v_mfma_f32_16x16x32_bf16 v[58:61], v[164:167], v[180:183], v[58:61]
	v_mfma_f32_16x16x32_bf16 v[50:53], v[172:175], v[180:183], v[50:53]
	v_mfma_f32_16x16x32_bf16 v[42:45], v[164:167], v[188:191], v[42:45]
	v_mfma_f32_16x16x32_bf16 v[34:37], v[172:175], v[188:191], v[34:37]
	v_mfma_f32_16x16x32_bf16 v[26:29], v[164:167], v[196:199], v[26:29]
	v_mfma_f32_16x16x32_bf16 v[18:21], v[172:175], v[196:199], v[18:21]
	v_mfma_f32_16x16x32_bf16 v[8:11], v[164:167], v[204:207], v[8:11]
	v_mfma_f32_16x16x32_bf16 v[0:3], v[172:175], v[204:207], v[0:3]
	s_setprio 0
	s_barrier
	s_add_i32 s62, s62, 2
	s_add_u32 s28, s28, 0x100
	s_addc_u32 s29, s29, 0
	s_add_u32 s60, s60, 0x100
	s_addc_u32 s61, s61, 0
	s_cmp_gt_u32 s62, 13
	s_cbranch_scc1 .Lpeel_exit_0

.Lpeel_exit_0:
	s_and_b64 vcc, exec, s[16:17]
	s_cbranch_vccz .LBB0_249
	s_barrier

.LBB0_566:
	s_ashr_i32 s27, s26, 31
	s_lshl_b64 s[28:29], s[26:27], 19
	s_add_u32 s28, s51, s28
	s_addc_u32 s29, s52, s29
	s_and_b64 s[30:31], s[6:7], exec
	s_cselect_b32 s1, s29, s11
	s_cselect_b32 s9, s28, s10
	s_ashr_i32 s25, s24, 31
	s_lshl_b64 s[30:31], s[24:25], 19
	s_add_u32 s30, s53, s30
	s_addc_u32 s31, s54, s31
	s_and_b64 s[34:35], s[6:7], exec
	s_cselect_b32 s25, s31, s13
	s_cselect_b32 s27, s30, s12
	s_add_u32 s10, s10, 0x40080
	s_addc_u32 s11, s11, 0
	s_add_u32 s36, s12, 0x100
	v_mov_b32_e32 v0, 0
	s_addc_u32 s37, s13, 0
	s_mov_b32 s38, -2
	s_add_u32 s12, s10, 0xfffc0080
	s_addc_u32 s13, s11, -1
	s_add_i32 s39, 0, 0x10000
	s_cmp_eq_u32 s38, 12
	s_cselect_b32 s35, s1, s13
	s_cselect_b32 s34, s9, s12
	v_add_u32_e32 v12, s39, v228
	s_cselect_b32 s13, s25, s37
	s_cselect_b32 s12, s27, s36
	s_add_i32 s46, 0, 0x14000
	ds_read_b128 v[130:133], v12
	ds_read_b128 v[134:137], v12 offset:1024
	ds_read_b128 v[138:141], v12 offset:2048
	ds_read_b128 v[142:145], v12 offset:3072
	v_add_u32_e32 v12, s46, v228
	ds_read_b128 v[146:149], v12
	ds_read_b128 v[150:153], v12 offset:1024
	ds_read_b128 v[154:157], v12 offset:2048
	ds_read_b128 v[158:161], v12 offset:3072
	v_lshl_add_u64 v[252:253], s[10:11], 0, v[208:209]
	s_add_i32 m0, s56, 0xc000
	ds_read_b128 v[162:165], v236
	ds_read_b128 v[166:169], v236 offset:1024
	ds_read_b128 v[170:173], v236 offset:2048
	ds_read_b128 v[174:177], v236 offset:3072
	ds_read_b128 v[212:215], v236 offset:4096
	ds_read_b128 v[240:243], v236 offset:5120
	ds_read_b128 v[244:247], v236 offset:6144
	ds_read_b128 v[248:251], v236 offset:7168
	global_load_lds_dwordx4 v[252:253], off
	v_lshl_add_u64 v[252:253], s[10:11], 0, v[210:211]
	s_add_i32 m0, s56, 0xe000
	s_nop 0
	global_load_lds_dwordx4 v[252:253], off
	s_waitcnt vmcnt(8)
	s_waitcnt lgkmcnt(0)
	s_barrier
	s_setprio 1
	s_waitcnt lgkmcnt(0)
	v_mfma_f32_16x16x32_bf16 v[126:129], v[130:133], v[162:165], 0
	v_mfma_f32_16x16x32_bf16 v[122:125], v[138:141], v[162:165], 0
	v_mfma_f32_16x16x32_bf16 v[118:121], v[130:133], v[170:173], 0
	v_mfma_f32_16x16x32_bf16 v[110:113], v[138:141], v[170:173], 0
	v_mfma_f32_16x16x32_bf16 v[102:105], v[130:133], v[212:215], 0
	v_mfma_f32_16x16x32_bf16 v[94:97], v[138:141], v[212:215], 0
	v_mfma_f32_16x16x32_bf16 v[86:89], v[130:133], v[244:247], 0
	v_mfma_f32_16x16x32_bf16 v[78:81], v[138:141], v[244:247], 0
	v_mfma_f32_16x16x32_bf16 v[126:129], v[134:137], v[166:169], v[126:129]
	v_mfma_f32_16x16x32_bf16 v[122:125], v[142:145], v[166:169], v[122:125]
	v_mfma_f32_16x16x32_bf16 v[118:121], v[134:137], v[174:177], v[118:121]
	v_mfma_f32_16x16x32_bf16 v[110:113], v[142:145], v[174:177], v[110:113]
	v_mfma_f32_16x16x32_bf16 v[102:105], v[134:137], v[240:243], v[102:105]
	v_mfma_f32_16x16x32_bf16 v[94:97], v[142:145], v[240:243], v[94:97]
	v_mfma_f32_16x16x32_bf16 v[86:89], v[134:137], v[248:251], v[86:89]
	v_mfma_f32_16x16x32_bf16 v[78:81], v[142:145], v[248:251], v[78:81]
	s_setprio 0
	s_setprio 1
	v_mfma_f32_16x16x32_bf16 v[114:117], v[146:149], v[162:165], 0
	v_mfma_f32_16x16x32_bf16 v[106:109], v[154:157], v[162:165], 0
	v_mfma_f32_16x16x32_bf16 v[98:101], v[146:149], v[170:173], 0
	v_mfma_f32_16x16x32_bf16 v[90:93], v[154:157], v[170:173], 0
	v_mfma_f32_16x16x32_bf16 v[82:85], v[146:149], v[212:215], 0
	v_mfma_f32_16x16x32_bf16 v[74:77], v[154:157], v[212:215], 0
	v_mfma_f32_16x16x32_bf16 v[70:73], v[146:149], v[244:247], 0
	v_mfma_f32_16x16x32_bf16 v[66:69], v[154:157], v[244:247], 0
	v_mfma_f32_16x16x32_bf16 v[114:117], v[150:153], v[166:169], v[114:117]
	v_mfma_f32_16x16x32_bf16 v[106:109], v[158:161], v[166:169], v[106:109]
	v_mfma_f32_16x16x32_bf16 v[98:101], v[150:153], v[174:177], v[98:101]
	v_mfma_f32_16x16x32_bf16 v[90:93], v[158:161], v[174:177], v[90:93]
	v_mfma_f32_16x16x32_bf16 v[82:85], v[150:153], v[240:243], v[82:85]
	v_mfma_f32_16x16x32_bf16 v[74:77], v[158:161], v[240:243], v[74:77]
	v_mfma_f32_16x16x32_bf16 v[70:73], v[150:153], v[248:251], v[70:73]
	v_mfma_f32_16x16x32_bf16 v[66:69], v[158:161], v[248:251], v[66:69]
	s_setprio 0
	s_barrier
	s_add_i32 s39, s39, s55
	v_lshl_add_u64 v[252:253], s[12:13], 0, v[180:181]
	s_mov_b32 m0, s39
	ds_read_b128 v[162:165], v236 offset:16384
	ds_read_b128 v[166:169], v236 offset:17408
	ds_read_b128 v[170:173], v236 offset:18432
	ds_read_b128 v[174:177], v236 offset:19456
	ds_read_b128 v[212:215], v236 offset:20480
	ds_read_b128 v[240:243], v236 offset:21504
	ds_read_b128 v[244:247], v236 offset:22528
	ds_read_b128 v[248:251], v236 offset:23552
	global_load_lds_dwordx4 v[252:253], off
	s_add_i32 m0, s39, 0x2000
	s_add_u32 s40, s12, 0x40000
	v_lshl_add_u64 v[220:221], s[12:13], 0, v[184:185]
	s_addc_u32 s41, s13, 0
	s_add_i32 s39, s46, s55
	global_load_lds_dwordx4 v[220:221], off
	v_lshl_add_u64 v[222:223], s[40:41], 0, v[180:181]
	s_mov_b32 m0, s39
	v_lshl_add_u64 v[224:225], s[34:35], 0, v[182:183]
	global_load_lds_dwordx4 v[222:223], off
	v_lshl_add_u64 v[222:223], s[40:41], 0, v[184:185]
	s_add_i32 m0, s39, 0x2000
	s_nop 0
	global_load_lds_dwordx4 v[222:223], off
	v_lshl_add_u64 v[222:223], s[34:35], 0, v[178:179]
	s_mov_b32 m0, s56
	s_nop 0
	global_load_lds_dwordx4 v[222:223], off
	s_mov_b32 m0, s57
	s_nop 0
	global_load_lds_dwordx4 v[224:225], off
	s_waitcnt vmcnt(8)
	s_waitcnt lgkmcnt(0)
	s_barrier
	s_setprio 1
	s_waitcnt lgkmcnt(0)
	v_mfma_f32_16x16x32_bf16 v[62:65], v[130:133], v[162:165], 0
	v_mfma_f32_16x16x32_bf16 v[58:61], v[138:141], v[162:165], 0
	v_mfma_f32_16x16x32_bf16 v[50:53], v[130:133], v[170:173], 0
	v_mfma_f32_16x16x32_bf16 v[42:45], v[138:141], v[170:173], 0
	v_mfma_f32_16x16x32_bf16 v[38:41], v[130:133], v[212:215], 0
	v_mfma_f32_16x16x32_bf16 v[30:33], v[138:141], v[212:215], 0
	v_mfma_f32_16x16x32_bf16 v[22:25], v[130:133], v[244:247], 0
	v_mfma_f32_16x16x32_bf16 v[14:17], v[138:141], v[244:247], 0
	v_mfma_f32_16x16x32_bf16 v[62:65], v[134:137], v[166:169], v[62:65]
	v_mfma_f32_16x16x32_bf16 v[58:61], v[142:145], v[166:169], v[58:61]
	v_mfma_f32_16x16x32_bf16 v[50:53], v[134:137], v[174:177], v[50:53]
	v_mfma_f32_16x16x32_bf16 v[42:45], v[142:145], v[174:177], v[42:45]
	v_mfma_f32_16x16x32_bf16 v[38:41], v[134:137], v[240:243], v[38:41]
	v_mfma_f32_16x16x32_bf16 v[30:33], v[142:145], v[240:243], v[30:33]
	v_mfma_f32_16x16x32_bf16 v[22:25], v[134:137], v[248:251], v[22:25]
	v_mfma_f32_16x16x32_bf16 v[14:17], v[142:145], v[248:251], v[14:17]
	s_setprio 0
	s_setprio 1
	v_mfma_f32_16x16x32_bf16 v[54:57], v[146:149], v[162:165], 0
	v_mfma_f32_16x16x32_bf16 v[46:49], v[154:157], v[162:165], 0
	v_mfma_f32_16x16x32_bf16 v[34:37], v[146:149], v[170:173], 0
	v_mfma_f32_16x16x32_bf16 v[26:29], v[154:157], v[170:173], 0
	v_mfma_f32_16x16x32_bf16 v[18:21], v[146:149], v[212:215], 0
	v_mfma_f32_16x16x32_bf16 v[8:11], v[154:157], v[212:215], 0
	v_mfma_f32_16x16x32_bf16 v[4:7], v[146:149], v[244:247], 0
	v_mfma_f32_16x16x32_bf16 v[0:3], v[154:157], v[244:247], 0
	v_mfma_f32_16x16x32_bf16 v[54:57], v[150:153], v[166:169], v[54:57]
	v_mfma_f32_16x16x32_bf16 v[46:49], v[158:161], v[166:169], v[46:49]
	v_mfma_f32_16x16x32_bf16 v[34:37], v[150:153], v[174:177], v[34:37]
	v_mfma_f32_16x16x32_bf16 v[26:29], v[158:161], v[174:177], v[26:29]
	v_mfma_f32_16x16x32_bf16 v[18:21], v[150:153], v[240:243], v[18:21]
	v_mfma_f32_16x16x32_bf16 v[8:11], v[158:161], v[240:243], v[8:11]
	v_mfma_f32_16x16x32_bf16 v[4:7], v[150:153], v[248:251], v[4:7]
	v_mfma_f32_16x16x32_bf16 v[0:3], v[158:161], v[248:251], v[0:3]
	s_setprio 0
	s_barrier
	s_add_i32 s39, 0, 0x18000
	v_add_u32_e32 v12, s39, v228
	s_add_i32 s40, 0, 0x1c000
	ds_read_b128 v[130:133], v12
	ds_read_b128 v[134:137], v12 offset:1024
	ds_read_b128 v[138:141], v12 offset:2048
	ds_read_b128 v[142:145], v12 offset:3072
	v_add_u32_e32 v12, s40, v228
	ds_read_b128 v[146:149], v12
	ds_read_b128 v[150:153], v12 offset:1024
	ds_read_b128 v[154:157], v12 offset:2048
	ds_read_b128 v[158:161], v12 offset:3072
	s_add_u32 s34, s34, 0x40000
	s_addc_u32 s35, s35, 0
	s_mov_b32 m0, s58
	v_lshl_add_u64 v[232:233], s[34:35], 0, v[178:179]
	ds_read_b128 v[162:165], v236 offset:32768
	ds_read_b128 v[166:169], v236 offset:33792
	ds_read_b128 v[170:173], v236 offset:34816
	ds_read_b128 v[174:177], v236 offset:35840
	ds_read_b128 v[212:215], v236 offset:36864
	ds_read_b128 v[240:243], v236 offset:37888
	ds_read_b128 v[244:247], v236 offset:38912
	ds_read_b128 v[248:251], v236 offset:39936
	global_load_lds_dwordx4 v[232:233], off
	v_lshl_add_u64 v[232:233], s[34:35], 0, v[182:183]
	s_mov_b32 m0, s59
	s_nop 0
	global_load_lds_dwordx4 v[232:233], off
	s_waitcnt vmcnt(8)
	s_waitcnt lgkmcnt(0)
	s_barrier
	s_setprio 1
	s_waitcnt lgkmcnt(0)
	v_mfma_f32_16x16x32_bf16 v[126:129], v[130:133], v[162:165], v[126:129]
	v_mfma_f32_16x16x32_bf16 v[122:125], v[138:141], v[162:165], v[122:125]
	v_mfma_f32_16x16x32_bf16 v[118:121], v[130:133], v[170:173], v[118:121]
	v_mfma_f32_16x16x32_bf16 v[110:113], v[138:141], v[170:173], v[110:113]
	v_mfma_f32_16x16x32_bf16 v[102:105], v[130:133], v[212:215], v[102:105]
	v_mfma_f32_16x16x32_bf16 v[94:97], v[138:141], v[212:215], v[94:97]
	v_mfma_f32_16x16x32_bf16 v[86:89], v[130:133], v[244:247], v[86:89]
	v_mfma_f32_16x16x32_bf16 v[78:81], v[138:141], v[244:247], v[78:81]
	v_mfma_f32_16x16x32_bf16 v[126:129], v[134:137], v[166:169], v[126:129]
	v_mfma_f32_16x16x32_bf16 v[122:125], v[142:145], v[166:169], v[122:125]
	v_mfma_f32_16x16x32_bf16 v[118:121], v[134:137], v[174:177], v[118:121]
	v_mfma_f32_16x16x32_bf16 v[110:113], v[142:145], v[174:177], v[110:113]
	v_mfma_f32_16x16x32_bf16 v[102:105], v[134:137], v[240:243], v[102:105]
	v_mfma_f32_16x16x32_bf16 v[94:97], v[142:145], v[240:243], v[94:97]
	v_mfma_f32_16x16x32_bf16 v[86:89], v[134:137], v[248:251], v[86:89]
	v_mfma_f32_16x16x32_bf16 v[78:81], v[142:145], v[248:251], v[78:81]
	s_setprio 0
	s_setprio 1
	v_mfma_f32_16x16x32_bf16 v[114:117], v[146:149], v[162:165], v[114:117]
	v_mfma_f32_16x16x32_bf16 v[106:109], v[154:157], v[162:165], v[106:109]
	v_mfma_f32_16x16x32_bf16 v[98:101], v[146:149], v[170:173], v[98:101]
	v_mfma_f32_16x16x32_bf16 v[90:93], v[154:157], v[170:173], v[90:93]
	v_mfma_f32_16x16x32_bf16 v[82:85], v[146:149], v[212:215], v[82:85]
	v_mfma_f32_16x16x32_bf16 v[74:77], v[154:157], v[212:215], v[74:77]
	v_mfma_f32_16x16x32_bf16 v[70:73], v[146:149], v[244:247], v[70:73]
	v_mfma_f32_16x16x32_bf16 v[66:69], v[154:157], v[244:247], v[66:69]
	v_mfma_f32_16x16x32_bf16 v[114:117], v[150:153], v[166:169], v[114:117]
	v_mfma_f32_16x16x32_bf16 v[106:109], v[158:161], v[166:169], v[106:109]
	v_mfma_f32_16x16x32_bf16 v[98:101], v[150:153], v[174:177], v[98:101]
	v_mfma_f32_16x16x32_bf16 v[90:93], v[158:161], v[174:177], v[90:93]
	v_mfma_f32_16x16x32_bf16 v[82:85], v[150:153], v[240:243], v[82:85]
	v_mfma_f32_16x16x32_bf16 v[74:77], v[158:161], v[240:243], v[74:77]
	v_mfma_f32_16x16x32_bf16 v[70:73], v[150:153], v[248:251], v[70:73]
	v_mfma_f32_16x16x32_bf16 v[66:69], v[158:161], v[248:251], v[66:69]
	s_setprio 0
	s_barrier
	s_add_i32 s34, s39, s55
	v_lshl_add_u64 v[232:233], v[252:253], 0, s[42:43]
	s_mov_b32 m0, s34
	ds_read_b128 v[162:165], v236 offset:49152
	ds_read_b128 v[166:169], v236 offset:50176
	ds_read_b128 v[170:173], v236 offset:51200
	ds_read_b128 v[174:177], v236 offset:52224
	ds_read_b128 v[212:215], v236 offset:53248
	ds_read_b128 v[240:243], v236 offset:54272
	ds_read_b128 v[244:247], v236 offset:55296
	ds_read_b128 v[248:251], v236 offset:56320
	global_load_lds_dwordx4 v[232:233], off
	s_add_i32 m0, s34, 0x2000
	s_add_u32 s12, s12, 0x40080
	v_lshl_add_u64 v[220:221], v[220:221], 0, s[42:43]
	s_addc_u32 s13, s13, 0
	s_add_i32 s34, s40, s55
	global_load_lds_dwordx4 v[220:221], off
	v_lshl_add_u64 v[220:221], s[12:13], 0, v[180:181]
	s_mov_b32 m0, s34
	s_nop 0
	global_load_lds_dwordx4 v[220:221], off
	v_lshl_add_u64 v[220:221], s[12:13], 0, v[184:185]
	s_add_i32 m0, s34, 0x2000
	s_nop 0
	global_load_lds_dwordx4 v[220:221], off
	v_lshl_add_u64 v[220:221], v[222:223], 0, s[42:43]
	s_mov_b32 m0, s65
	s_nop 0
	global_load_lds_dwordx4 v[220:221], off
	v_lshl_add_u64 v[220:221], v[224:225], 0, s[42:43]
	s_mov_b32 m0, s66
	s_nop 0
	global_load_lds_dwordx4 v[220:221], off
	s_waitcnt vmcnt(8)
	s_waitcnt lgkmcnt(0)
	s_barrier
	s_setprio 1
	s_waitcnt lgkmcnt(0)
	v_mfma_f32_16x16x32_bf16 v[62:65], v[130:133], v[162:165], v[62:65]
	v_mfma_f32_16x16x32_bf16 v[58:61], v[138:141], v[162:165], v[58:61]
	v_mfma_f32_16x16x32_bf16 v[50:53], v[130:133], v[170:173], v[50:53]
	v_mfma_f32_16x16x32_bf16 v[42:45], v[138:141], v[170:173], v[42:45]
	v_mfma_f32_16x16x32_bf16 v[38:41], v[130:133], v[212:215], v[38:41]
	v_mfma_f32_16x16x32_bf16 v[30:33], v[138:141], v[212:215], v[30:33]
	v_mfma_f32_16x16x32_bf16 v[22:25], v[130:133], v[244:247], v[22:25]
	v_mfma_f32_16x16x32_bf16 v[14:17], v[138:141], v[244:247], v[14:17]
	v_mfma_f32_16x16x32_bf16 v[62:65], v[134:137], v[166:169], v[62:65]
	v_mfma_f32_16x16x32_bf16 v[58:61], v[142:145], v[166:169], v[58:61]
	v_mfma_f32_16x16x32_bf16 v[50:53], v[134:137], v[174:177], v[50:53]
	v_mfma_f32_16x16x32_bf16 v[42:45], v[142:145], v[174:177], v[42:45]
	v_mfma_f32_16x16x32_bf16 v[38:41], v[134:137], v[240:243], v[38:41]
	v_mfma_f32_16x16x32_bf16 v[30:33], v[142:145], v[240:243], v[30:33]
	v_mfma_f32_16x16x32_bf16 v[22:25], v[134:137], v[248:251], v[22:25]
	v_mfma_f32_16x16x32_bf16 v[14:17], v[142:145], v[248:251], v[14:17]
	s_setprio 0
	s_setprio 1
	v_mfma_f32_16x16x32_bf16 v[54:57], v[146:149], v[162:165], v[54:57]
	v_mfma_f32_16x16x32_bf16 v[46:49], v[154:157], v[162:165], v[46:49]
	v_mfma_f32_16x16x32_bf16 v[34:37], v[146:149], v[170:173], v[34:37]
	v_mfma_f32_16x16x32_bf16 v[26:29], v[154:157], v[170:173], v[26:29]
	v_mfma_f32_16x16x32_bf16 v[18:21], v[146:149], v[212:215], v[18:21]
	v_mfma_f32_16x16x32_bf16 v[8:11], v[154:157], v[212:215], v[8:11]
	v_mfma_f32_16x16x32_bf16 v[4:7], v[146:149], v[244:247], v[4:7]
	v_mfma_f32_16x16x32_bf16 v[0:3], v[154:157], v[244:247], v[0:3]
	v_mfma_f32_16x16x32_bf16 v[54:57], v[150:153], v[166:169], v[54:57]
	v_mfma_f32_16x16x32_bf16 v[46:49], v[158:161], v[166:169], v[46:49]
	v_mfma_f32_16x16x32_bf16 v[34:37], v[150:153], v[174:177], v[34:37]
	v_mfma_f32_16x16x32_bf16 v[26:29], v[158:161], v[174:177], v[26:29]
	v_mfma_f32_16x16x32_bf16 v[18:21], v[150:153], v[240:243], v[18:21]
	v_mfma_f32_16x16x32_bf16 v[8:11], v[158:161], v[240:243], v[8:11]
	v_mfma_f32_16x16x32_bf16 v[4:7], v[150:153], v[248:251], v[4:7]
	v_mfma_f32_16x16x32_bf16 v[0:3], v[158:161], v[248:251], v[0:3]
	s_setprio 0
	s_barrier
	s_add_i32 s38, s38, 2
	s_add_u32 s10, s10, 0x100
	s_addc_u32 s11, s11, 0
	s_add_u32 s36, s36, 0x100
	s_addc_u32 s37, s37, 0
	s_cmp_gt_u32 s38, 13
	s_cbranch_scc1 .Lpeel_exit_1

.Lpeel_exit_1:
	s_and_b64 vcc, exec, s[22:23]
	s_cbranch_vccz .LBB0_570
	s_barrier
